# FFN-up idle WG extras 4 (with sc1 nt loads)
# speedup vs baseline: 1.0004x; 1.0004x over previous
; __global__ void __launch_bounds__(NWAVES * 64, 2) mega_fwd(Args A) {
;     ...
;     float* X = (float*)(ws + WS_X); bf16* H = (bf16*)(ws + WS_H); bf16* ACT = (bf16*)(ws + WS_ACT); bf16* PROJ = (bf16*)(ws + WS_PROJ);
;     bf16* Y = (bf16*)(ws + WS_Y); float* MACC = (float*)(ws + WS_MACC); bf16* MB = (bf16*)(ws + WS_MB); float* GO = (float*)(ws + WS_GO);
;     const float* COS = (const float*)(ws + WS_ROPE); const float* SIN = COS + (size_t)NTOK * 32;
;     { int t_ = threadIdx.x; asm volatile("" : "+v"(t_)); const int w_ = __builtin_amdgcn_readfirstlane(t_ >> 6); p0_prologue(A, lds, bx * NWAVES + w_, G * NWAVES, w_, t_ & 63); }
;     conv_until(A, lds, TL_WO1, 0);
;     xcd_barrier(bar);
; #pragma unroll 1
;     for (int step = 0; step < 3 * DEPTH; ++step) {
;         const int l = step / 3, kind = step - 3 * l;
;         unsigned char* wl = ws + WS_W + (size_t)l * LW_END;
;         const unsigned long long* ssq = (const unsigned long long*)(ws + WS_CTL + CTL_SSQ) + (size_t)step * NTOK; unsigned long long* ssq_next = (unsigned long long*)(ws + WS_CTL + CTL_SSQ) + (size_t)(step + 1) * NTOK;
;         if (kind != 1) {
;             { pg8::Gemm g{H, (const bf16*)(wl + (kind == 0 ? LW_WI1 : LW_WI2)), NTOK, NWI, DM}; pg8::StaticOrder S; S.init(NTOK, NWI, G, bx);
;               pg8::EpiSwiglu E{ACT, DFF, ssq};
;               pg8::gemm_phase<pg8::EpiSwiglu, pg8::StaticOrder, true, true>(lds + RING_OFF, g, S, E); }
;             { const int rem1 = ((NTOK / 256) * (NWI / 256)) % G;
;               conv_until(A, lds, l * TL_LAYER + (kind == 0 ? TL_WIN : TL_LAYER), (rem1 != 0 && bx >= rem1) ? 3 : 0); }
;             xcd_barrier(bar);
;         } else {
;             const bool std256 = (G == 256);
;             unsigned char* XB8 = ws + WS_X;
; #pragma unroll 1
;             for (int part = 0; part < 3; ++part) {
;                 bool do16, do8; int i16, n16, g8, c8, i8, n8;
;                 if (std256) { do16 = part == 0 || (part == 1 && bx < 64); i16 = part ? 2 : 0; n16 = part ? 1 : 2;
;                               do8 = (part == 1 && bx >= 64) || (part == 2 && bx < 128); g8 = part == 1 ? 192 : 128; c8 = part == 1 ? bx - 64 : bx; i8 = part == 1 ? 0 : 3; n8 = part == 1 ? 2 : 3; }
;                 else { do16 = part == 0; i16 = 0; n16 = 1 << 20; do8 = part == 1; g8 = G; c8 = bx; i8 = 0; n8 = 1 << 20; }
.LBB0_284:
	v_writelane_b32 v252, s64, 42
	s_nop 1
	v_writelane_b32 v252, s65, 43
	v_writelane_b32 v252, s66, 44
	v_writelane_b32 v252, s67, 45
	v_writelane_b32 v252, s68, 46
	v_writelane_b32 v252, s69, 47
	v_writelane_b32 v252, s70, 48
	v_writelane_b32 v252, s71, 49
	v_writelane_b32 v252, s72, 50
	v_writelane_b32 v252, s73, 51
	v_writelane_b32 v252, s74, 52
	v_writelane_b32 v252, s75, 53
	v_writelane_b32 v252, s76, 54
	v_writelane_b32 v252, s77, 55
	v_writelane_b32 v252, s78, 56
	v_writelane_b32 v252, s79, 57
	s_or_b64 exec, exec, s[0:1]
	s_cmpk_lg_i32 s95, 0x100
	s_cselect_b64 s[0:1], -1, 0
	s_and_b64 s[0:1], s[0:1], exec
	s_cselect_b32 s69, s95, 0x80
	s_add_i32 s4, s97, 0xffffff80
	s_cmpk_lg_i32 s95, 0x100
	s_cselect_b64 s[0:1], -1, 0
	s_and_b64 s[2:3], s[0:1], exec
	s_cselect_b32 s20, s97, s4
	v_readlane_b32 s4, v252, 2
	v_readlane_b32 s18, v252, 16
	v_readlane_b32 s19, v252, 17
	s_add_u32 s74, s18, 0x10000
	s_addc_u32 s2, s19, 0
	v_readlane_b32 s5, v252, 3
	v_readlane_b32 s6, v252, 4
	v_readlane_b32 s7, v252, 5
	v_readlane_b32 s8, v252, 6
	v_readlane_b32 s9, v252, 7
	v_readlane_b32 s10, v252, 8
	v_readlane_b32 s11, v252, 9
	v_readlane_b32 s12, v252, 10
	v_readlane_b32 s13, v252, 11
	v_readlane_b32 s14, v252, 12
	v_readlane_b32 s15, v252, 13
	v_readlane_b32 s16, v252, 14
	v_readlane_b32 s17, v252, 15
	v_writelane_b32 v252, s2, 58
	s_add_u32 s2, s18, 0x35e00000
	s_addc_u32 s3, s19, 0
	s_add_u32 s88, s18, 0x3b600000
	s_addc_u32 s89, s19, 0
	v_writelane_b32 v252, s2, 59
	s_add_u32 s12, s18, 0x45e00000
	s_addc_u32 s13, s19, 0
	v_writelane_b32 v252, s3, 60
	v_writelane_b32 v252, s12, 61
	s_add_u32 s2, s18, 0x4c200000
	v_writelane_b32 v252, s13, 62
	s_addc_u32 s3, s19, 0
	v_writelane_b32 v252, s2, 63
	s_waitcnt vmcnt(15)
	v_mov_b32_e32 v3, 0
	v_mov_b32_e32 v216, 1
	v_writelane_b32 v253, s3, 0
	s_add_u32 s2, s18, 0x4e200000
	s_addc_u32 s3, s19, 0
	v_writelane_b32 v253, s2, 1
	v_mov_b32_e32 v217, 0x7f7f7f7f
	v_mov_b32_e32 v225, 0x43e00000
	v_writelane_b32 v253, s3, 2
	s_add_u32 s2, s18, 0x4fa00000
	s_addc_u32 s3, s19, 0
	v_writelane_b32 v253, s2, 3
	v_mov_b64_e32 v[226:227], 0x2ff
	v_mov_b32_e32 v222, 0x41b17218
	v_writelane_b32 v253, s3, 4
	s_add_u32 s2, s18, 0x4fb00000
	s_addc_u32 s3, s19, 0
	v_writelane_b32 v253, s2, 5
	v_mbcnt_hi_u32_b32 v223, -1, v76
	v_mov_b32_e32 v224, 0xf149f2ca
	v_writelane_b32 v253, s3, 6
	s_add_u32 s2, s18, 0x200000
	v_writelane_b32 v253, s2, 7
	s_addc_u32 s2, s19, 0
	s_cmpk_lt_i32 s97, 0x580
	v_writelane_b32 v253, s2, 8
	s_cselect_b64 s[2:3], -1, 0
	v_writelane_b32 v253, s2, 9
	s_ashr_i32 s21, s97, 31
	s_movk_i32 s75, 0xc0
	v_writelane_b32 v253, s3, 10
	s_lshr_b32 s2, s21, 29
	s_add_i32 s3, s97, s2
	s_ashr_i32 s2, s3, 3
	s_and_b32 s3, s3, -8
	s_sub_i32 s5, s97, s3
	s_ashr_i32 s3, s95, 31
	s_add_u32 s6, s18, 0x4200
	v_writelane_b32 v253, s3, 11
	s_addc_u32 s7, s19, 0
	v_writelane_b32 v253, s6, 12
	s_movk_i32 s76, 0x300
	s_movk_i32 s77, 0x5400
	v_writelane_b32 v253, s7, 13
	s_add_u32 s6, s18, 0x4400
	s_addc_u32 s7, s19, 0
	v_writelane_b32 v253, s6, 14
	s_movk_i32 s81, 0x7fff
	s_mov_b32 s82, 0xffff0000
	v_writelane_b32 v253, s7, 15
	s_add_u32 s6, s18, 0x4500
	s_addc_u32 s7, s19, 0
	v_writelane_b32 v253, s6, 16
	s_movk_i32 s61, 0x1110
	s_movk_i32 s84, 0x15ff
	v_writelane_b32 v253, s7, 17
	s_add_u32 s6, s18, 0x4600
	s_addc_u32 s7, s19, 0
	v_writelane_b32 v253, s6, 18
	s_mov_b32 s85, 0xc3e00000
	s_movk_i32 s33, 0xff
	v_writelane_b32 v253, s7, 19
	s_add_u32 s6, s18, 0x4700
	s_addc_u32 s7, s19, 0
	v_writelane_b32 v253, s6, 20
	s_movk_i32 s66, 0x90
	s_mov_b32 s96, 0x2aaaaaab
	v_writelane_b32 v253, s7, 21
	s_add_u32 s6, s18, 0x4800
	s_addc_u32 s7, s19, 0
	v_writelane_b32 v253, s6, 22
	s_movk_i32 s36, 0x190
	s_movk_i32 s37, 0xff40
	v_writelane_b32 v253, s7, 23
	s_add_u32 s6, s18, 0x4900
	s_addc_u32 s7, s19, 0
	v_writelane_b32 v253, s6, 24
	s_movk_i32 s38, 0x567
	s_movk_i32 s39, 0x1500
	v_writelane_b32 v253, s7, 25
	s_add_u32 s6, s18, 0x4a00
	s_addc_u32 s7, s19, 0
	v_writelane_b32 v253, s6, 26
	s_movk_i32 s56, 0x1800
	s_movk_i32 s57, 0xc80
	v_writelane_b32 v253, s7, 27
	s_add_u32 s6, s18, 0x4b00
	s_addc_u32 s7, s19, 0
	v_writelane_b32 v253, s6, 28
	s_movk_i32 s58, 0x3ff
	s_mov_b32 s80, 0xefa18f08
	v_writelane_b32 v253, s7, 29
	s_add_u32 s6, s18, 0x4c00
	s_addc_u32 s7, s19, 0
	v_writelane_b32 v253, s6, 30
	s_mov_b32 s62, 0
	s_mov_b32 s94, 0x3e000000
	v_writelane_b32 v253, s7, 31
	s_add_u32 s6, s18, 0x4d00
	s_addc_u32 s7, s19, 0
	v_writelane_b32 v253, s6, 32
	s_waitcnt lgkmcnt(0)
	s_barrier
; __global__ void __launch_bounds__(NWAVES * 64, 2) mega_fwd(Args A) {
;     ...
;                 if (std256) { do16 = part == 0 || (part == 1 && bx < 64); i16 = part ? 2 : 0; n16 = part ? 1 : 2;
;                               do8 = (part == 1 && bx >= 64) || (part == 2 && bx < 128); g8 = part == 1 ? 192 : 128; c8 = part == 1 ? bx - 64 : bx; i8 = part == 1 ? 0 : 3; n8 = part == 1 ? 2 : 3; }
;                 else { do16 = part == 0; i16 = 0; n16 = 1 << 20; do8 = part == 1; g8 = G; c8 = bx; i8 = 0; n8 = 1 << 20; }
;                 if (do16) { pg8::Gemm g{H, (const bf16*)(wl + LW_WIN), NTOK, C_GATE, DM}; pg8::RangeOrder S; S.init(NTOK, C_GATE, G, bx); S.i0 = i16; S.n = n16;
;                     pg8::EpiProj E{PROJ, NPROJ, (const float*)A.in[7] + (size_t)l * 6144, 1 << 20, ssq, 1.0f};
;                     pg8::gemm_phase<pg8::EpiProj, pg8::RangeOrder, true, true>(lds + RING_OFF, g, S, E); }
;                 if (do8) { pg8::Gemm g{(const bf16*)XB8, (const bf16*)(wl + LW_WIN + WIN8_OFF), NTOK, 6144, DM / 2}; pg8::RangeOrder S; S.init(NTOK, 6144, g8, c8); S.i0 = i8; S.n = n8;
;                     pg8::EpiGate8 E{(unsigned char*)(PROJ + C_GATE), NPROJ * 2, (const float*)A.in[7] + (size_t)l * 6144, ssq, 1.0f / 2048.0f};
;                     pg8::gemm_phase<pg8::EpiGate8, pg8::RangeOrder, true, true, true>(lds + RING_OFF, g, S, E); }
;                 if (part == 1) xcd_barrier(bar);
;                 if (part == 2 && (!std256 || bx >= 128)) { const int mb = std256 ? bx - 128 : bx, ms = std256 ? 128 : G;
;                     if ((ms & 3) == 0) pool_units(lds, PROJ, (const bf16*)(ws + WS_WPT) + (size_t)l * 4 * 192 * 192, Y + (size_t)NTOK * BRW, mb, ms, 512);
;                     else for (int u = mb; u < 512; u += ms) pool_units(lds, PROJ, (const bf16*)(ws + WS_WPT) + (size_t)l * 4 * 192 * 192, Y + (size_t)NTOK * BRW, u, 512, 512);
;                     gla_pre_items(lds, PROJ, (const float*)A.in[11] + (size_t)l * 16 * 384, (const float*)A.in[12] + l * 384, ws + WS_GPRE, mb, ms, 512); }
;             }
;             xcd_barrier(bar);
;             if (G > 96) { if (bx < 48) gla_scan_unit(lds, ws + WS_GPRE, GO, bx);
;                           else for (int u = bx - 48; u < 256; u += G - 48) att_unit(lds, PROJ, COS, SIN, (const float*)A.in[8] + l * 12, Y, u); }
;             else { for (int u = bx; u < 48; u += G) gla_scan_unit(lds, ws + WS_GPRE, GO, u);
	v_writelane_b32 v253, s7, 33
	s_add_u32 s6, s18, 0x4e00
	s_addc_u32 s7, s19, 0
	v_writelane_b32 v253, s6, 34
	s_nop 1
	v_writelane_b32 v253, s7, 35
	s_add_u32 s6, s18, 0x4f00
	s_addc_u32 s7, s19, 0
	v_writelane_b32 v253, s6, 36
	s_nop 1
	v_writelane_b32 v253, s7, 37
	s_add_u32 s6, s18, 0x5000
	s_addc_u32 s7, s19, 0
	v_writelane_b32 v253, s6, 38
	s_nop 1
	v_writelane_b32 v253, s7, 39
	s_add_u32 s6, s18, 0x5100
	s_addc_u32 s7, s19, 0
	v_writelane_b32 v253, s6, 40
	s_nop 1
	v_writelane_b32 v253, s7, 41
	s_add_u32 s6, s18, 0x5200
	s_addc_u32 s7, s19, 0
	v_writelane_b32 v253, s6, 42
	s_nop 1
	v_writelane_b32 v253, s7, 43
	s_add_u32 s6, s18, 0x5300
	s_addc_u32 s7, s19, 0
	v_writelane_b32 v253, s6, 44
	s_nop 1
	v_writelane_b32 v253, s7, 45
	s_add_u32 s6, s18, 0x7400
	s_addc_u32 s7, s19, 0
	v_writelane_b32 v253, s6, 46
	s_nop 1
	v_writelane_b32 v253, s7, 47
	s_add_u32 s6, s18, 0x7500
	s_addc_u32 s7, s19, 0
	v_writelane_b32 v253, s6, 48
	s_cmpk_eq_i32 s95, 0x100
	s_nop 0
	v_writelane_b32 v253, s7, 49
	s_cselect_b64 s[6:7], -1, 0
	s_add_u32 s72, s18, 0x2fe00000
	s_addc_u32 s73, s19, 0
	v_writelane_b32 v253, s6, 50
	s_cmp_lt_i32 s97, 64
	s_nop 0
	v_writelane_b32 v253, s7, 51
	s_cselect_b64 s[6:7], -1, 0
	v_writelane_b32 v253, s6, 52
	s_cmp_gt_i32 s97, 63
	s_nop 0
	v_writelane_b32 v253, s7, 53
	s_cselect_b64 s[6:7], -1, 0
	v_writelane_b32 v253, s6, 54
	s_cmpk_lt_i32 s97, 0x80
	s_nop 0
	v_writelane_b32 v253, s7, 55
	s_cselect_b64 s[6:7], -1, 0
	v_writelane_b32 v253, s6, 56
	s_sub_i32 s3, s97, 64
	s_nop 0
	v_writelane_b32 v253, s7, 57
	s_add_u32 s6, s18, 0x3b602400
	v_writelane_b32 v253, s3, 58
	s_addc_u32 s7, s19, 0
	v_writelane_b32 v253, s6, 59
	s_cmpk_gt_i32 s97, 0x7f
	s_nop 0
	v_writelane_b32 v253, s7, 60
	s_cselect_b64 s[6:7], -1, 0
	s_or_b64 s[0:1], s[6:7], s[0:1]
	v_writelane_b32 v253, s0, 61
	s_nop 1
	v_writelane_b32 v253, s1, 62
	s_and_b32 s0, s69, 3
	s_cmp_lg_u32 s0, 0
	s_cselect_b64 s[0:1], -1, 0
	v_writelane_b32 v253, s0, 63
	s_cmpk_lt_i32 s20, 0x200
	s_nop 0
	v_writelane_b32 v254, s1, 0
	s_cselect_b64 s[0:1], -1, 0
	v_writelane_b32 v254, s0, 1
	s_nop 1
	v_writelane_b32 v254, s1, 2
	s_add_u32 s0, s18, 0x46a00000
	s_addc_u32 s1, s19, 0
	v_writelane_b32 v254, s0, 3
	s_and_b32 s4, s20, 3
	s_nop 0
	v_writelane_b32 v254, s1, 4
	s_mul_i32 s0, s4, 0x12000
	s_add_u32 s0, s34, s0
	v_writelane_b32 v254, s0, 5
	v_writelane_b32 v254, s34, 6
	s_addc_u32 s0, s35, 0
	s_lshl_b32 s68, 2, s4
	v_writelane_b32 v254, s35, 7
	v_writelane_b32 v254, s0, 8
	s_lshl_b32 s1, s20, 4
	s_lshl_b32 s0, s69, 4
	s_add_u32 s22, s18, 0x4fc00000
	v_writelane_b32 v254, s0, 9
	s_addc_u32 s23, s19, 0
	s_lshl_b32 s0, s20, 6
	s_and_b32 s0, s0, 0x7c0
	v_writelane_b32 v254, s1, 10
	s_and_b32 s1, s1, 0xfffff800
	s_or_b32 s0, s1, s0
	s_ashr_i32 s1, s0, 31
	v_writelane_b32 v254, s0, 11
	s_bfe_u32 s3, s20, 0x20005
	s_mov_b32 s35, 0
	v_writelane_b32 v254, s1, 12
	s_mul_i32 s0, s3, 0x60
	v_writelane_b32 v254, s20, 13
	s_add_i32 s1, s0, 0x920
	v_writelane_b32 v254, s1, 14
	v_writelane_b32 v254, s0, 15
	s_bitset1_b32 s0, 11
	s_cmpk_lt_i32 s95, 0x61
	v_writelane_b32 v254, s0, 16
	s_cselect_b64 s[0:1], -1, 0
	s_cmpk_gt_i32 s95, 0x60
	v_writelane_b32 v254, s0, 17
	s_cselect_b64 s[6:7], -1, 0
	s_cmp_lt_i32 s97, 48
	v_writelane_b32 v254, s1, 18
	s_cselect_b64 s[0:1], -1, 0
	v_writelane_b32 v254, s0, 19
	s_cmpk_lt_i32 s97, 0x100
	s_nop 0
	v_writelane_b32 v254, s1, 20
	s_cselect_b64 s[0:1], -1, 0
	v_writelane_b32 v254, s0, 21
	s_nop 1
	v_writelane_b32 v254, s1, 22
	s_sub_i32 s0, s97, 48
	v_writelane_b32 v254, s0, 23
	s_cmpk_lt_i32 s97, 0x130
	s_mul_hi_i32 s0, s97, 0x55555556
	s_cselect_b64 s[8:9], -1, 0
	s_lshr_b32 s1, s0, 31
	s_add_i32 s10, s0, s1
	s_mul_i32 s0, s10, -3
	s_add_i32 s0, s0, s97
	v_writelane_b32 v254, s8, 24
	s_lshl_b32 s1, s0, 13
	s_add_i32 s1, s1, 0x8000
	v_writelane_b32 v254, s9, 25
	v_writelane_b32 v254, s1, 26
	s_sub_i32 s1, s95, 48
	v_writelane_b32 v254, s1, 27
	s_lshl_b32 s8, s10, 5
	s_mul_i32 s1, s10, 0x1c4000
	v_writelane_b32 v254, s8, 28
	s_mul_hi_i32 s8, s8, 0xe200
	s_add_u32 s14, s22, s1
	s_addc_u32 s15, s23, s8
	s_add_u32 s8, s14, 0xe000
	v_writelane_b32 v254, s14, 29
	s_addc_u32 s9, s15, 0
	s_lshl_b32 s1, s10, 9
	s_lshl_b32 s0, s0, 6
	v_writelane_b32 v254, s15, 30
	s_and_b32 s11, s1, 0xfffff800
	s_ashr_i32 s1, s0, 31
	v_writelane_b32 v254, s8, 31
	s_cmp_gt_i32 s97, 47
	s_nop 0
	v_writelane_b32 v254, s9, 32
	s_cselect_b64 s[8:9], -1, 0
	v_writelane_b32 v254, s8, 33
	s_mov_b64 s[14:15], s[6:7]
	s_add_i32 s6, s97, s95
	s_addk_i32 s6, 0xffa0
	v_writelane_b32 v254, s9, 34
	s_cmpk_lt_i32 s6, 0x100
	s_cselect_b32 s8, 2, 4
	v_writelane_b32 v254, s14, 35
	s_and_b64 s[6:7], s[14:15], exec
	s_cselect_b32 s6, s8, 0
	v_writelane_b32 v254, s15, 36
	v_writelane_b32 v254, s6, 37
	s_add_u32 s6, s18, 0x47600000
	v_writelane_b32 v254, s6, 38
	s_addc_u32 s6, s19, 0
	v_writelane_b32 v254, s6, 39
	s_lshl_b32 s14, s95, 5
	s_lshl_b32 s6, s5, 5
	s_cmp_lt_i32 s5, 0
	s_movk_i32 s7, 0xb1
;     __host__ __device__ bool next(int i, Unit& u) const {
;         const long L = (long)i * G + c; if (L >= nwg) return false;
;         int wgid = (int)L; { const int q = nwg / NXCD, r = nwg % NXCD, xcd = wgid % NXCD, off = wgid / NXCD; wgid = (xcd < r ? xcd * (q + 1) : r * (q + 1) + (xcd - r) * q) + off; }
;         const int nig = WGM * nN, gid = wgid / nig, fm = gid * WGM, gsz = (nM - fm) < WGM ? (nM - fm) : WGM;
;         u.pm = fm + ((wgid % nig) % gsz); u.pn = (wgid % nig) / gsz; u.seg = 0; return true;
; __global__ void __launch_bounds__(NWAVES * 64, 2) mega_fwd(Args A) {
;     ...
;             { const int rem1 = ((NTOK / 256) * (NWI / 256)) % G;
;               conv_until(A, lds, l * TL_LAYER + (kind == 0 ? TL_WIN : TL_LAYER), (rem1 != 0 && bx >= rem1) ? 3 : 0); }
	s_cselect_b32 s7, s7, 0xb0
	s_mul_i32 s7, s5, s7
	s_mul_i32 s5, s5, 33
	s_cselect_b32 s5, s5, s6
	s_add_i32 s7, s7, s2
	s_mul_hi_i32 s6, s7, 0x2e8ba2e9
	s_lshr_b32 s8, s6, 31
	s_ashr_i32 s6, s6, 6
	s_add_i32 s6, s6, s8
	s_mul_i32 s8, s6, 0x160
	s_sub_i32 s7, s7, s8
	s_bfe_u32 s8, s7, 0x3001c
	s_add_i32 s8, s7, s8
	s_and_b32 s9, s8, 0xfff8
	s_sub_i32 s7, s7, s9
	s_lshl_b32 s6, s6, 3
	s_sext_i32_i16 s8, s8
	s_sext_i32_i16 s7, s7
	s_add_i32 s16, s6, s7
	s_ashr_i32 s6, s8, 3
	v_writelane_b32 v254, s6, 40
	s_lshr_b32 s6, s8, 3
	s_bfe_i64 s[6:7], s[6:7], 0x100000
	s_lshl_b64 s[6:7], s[6:7], 20
	v_writelane_b32 v254, s6, 41
	s_ashr_i32 s17, s16, 31
	s_nop 0
	v_writelane_b32 v254, s7, 42
	s_mov_b32 s6, s16
	v_writelane_b32 v254, s6, 43
	s_nop 1
	v_writelane_b32 v254, s7, 44
	s_lshl_b64 s[6:7], s[16:17], 20
	s_add_u32 s6, s90, s6
	s_addc_u32 s7, s91, s7
	s_add_u32 s8, s6, 0x80000
	s_addc_u32 s9, s7, 0
	v_writelane_b32 v254, s8, 45
	s_nop 1
	v_writelane_b32 v254, s9, 46
	s_add_u32 s8, s6, 0x2000
	v_writelane_b32 v254, s6, 47
	s_addc_u32 s9, s7, 0
	s_add_i32 s2, s5, s2
	s_ashr_i32 s5, s2, 31
	s_lshr_b32 s5, s5, 26
	s_add_i32 s5, s2, s5
	v_writelane_b32 v254, s7, 48
	s_and_b32 s6, s5, 0xffc0
	s_sub_i32 s2, s2, s6
	s_bfe_i32 s6, s2, 0x80000
	s_bfe_u32 s6, s6, 0x3000c
	s_add_i32 s6, s2, s6
	s_and_b32 s7, s6, 0xf8
	s_sub_i32 s2, s2, s7
	s_ashr_i32 s5, s5, 6
	s_lshl_b32 s5, s5, 3
	s_sext_i32_i8 s2, s2
	s_add_i32 s5, s5, s2
	s_bfe_i32 s2, s6, 0x80000
	v_writelane_b32 v254, s8, 49
	s_sext_i32_i16 s2, s2
	s_ashr_i32 s6, s2, 3
	v_writelane_b32 v254, s9, 50
	s_lshr_b32 s2, s2, 3
	v_writelane_b32 v254, s6, 51
	s_bfe_i64 s[6:7], s[2:3], 0x100000
	v_writelane_b32 v254, s6, 52
	s_mul_hi_i32 s2, s5, 0x60000
	s_nop 0
	v_writelane_b32 v254, s7, 53
	v_writelane_b32 v254, s5, 54
	s_mul_i32 s5, s5, 0x60000
	s_add_u32 s6, s12, s5
	s_addc_u32 s7, s13, s2
	s_add_u32 s8, s6, 0x30000
	s_addc_u32 s9, s7, 0
	v_writelane_b32 v254, s8, 55
	s_nop 1
	v_writelane_b32 v254, s9, 56
	s_add_u32 s8, s6, 0x2000
	v_writelane_b32 v254, s6, 57
	s_addc_u32 s9, s7, 0
	s_abs_i32 s2, s95
	v_cvt_f32_u32_e32 v1, s2
	v_writelane_b32 v254, s7, 58
	s_sub_i32 s5, 0, s2
	v_writelane_b32 v254, s8, 59
	v_rcp_iflag_f32_e32 v1, v1
	s_nop 0
	v_writelane_b32 v254, s9, 60
	v_mul_f32_e32 v1, 0x4f7ffffe, v1
	v_cvt_u32_f32_e32 v1, v1
	s_nop 0
	v_readfirstlane_b32 s6, v1
	s_mul_i32 s5, s5, s6
	s_mul_hi_u32 s5, s6, s5
	s_add_i32 s6, s6, s5
	s_mul_hi_u32 s5, s6, 0x580
	s_mul_i32 s5, s5, s2
	s_sub_i32 s5, 0x580, s5
	s_sub_i32 s6, s5, s2
	s_cmp_ge_u32 s5, s2
	s_cselect_b32 s5, s6, s5
	s_sub_i32 s6, s5, s2
	s_cmp_ge_u32 s5, s2
	s_cselect_b32 s2, s6, s5
	s_cmp_lg_u32 s2, 0
	s_cselect_b64 s[6:7], -1, 0
	s_cmp_ge_i32 s97, s2
	s_cselect_b64 s[8:9], -1, 0
	s_and_b64 s[6:7], s[6:7], s[8:9]
	s_mul_i32 s2, s4, 0xc0
	v_writelane_b32 v254, s6, 61
	s_and_b64 s[4:5], s[6:7], exec
	s_cselect_b32 s4, 4, 0
	v_writelane_b32 v254, s7, 62
	v_writelane_b32 v255, s2, 0
	s_lshl_b32 s2, s2, 1
	v_writelane_b32 v254, s4, 63
	s_add_u32 s4, s88, s2
	s_addc_u32 s5, s89, 0
	v_writelane_b32 v255, s4, 1
	s_and_b32 s2, s10, 3
	s_mulk_i32 s2, 0x300
	v_writelane_b32 v255, s5, 2
	s_mul_i32 s4, s11, 0xc00
	s_lshl_b32 s5, s97, 6
	s_or_b32 s2, s4, s2
	s_lshl_b64 s[0:1], s[0:1], 2
	v_writelane_b32 v255, s5, 3
	s_lshl_b32 s5, s95, 6
	s_mul_hi_i32 s4, s11, 0xc00
	s_add_u32 s0, s2, s0
	s_addc_u32 s1, s4, s1
	s_add_u32 s0, s18, s0
	v_writelane_b32 v255, s5, 4
	s_addc_u32 s1, s19, s1
	v_writelane_b32 v255, s0, 5
	s_mul_i32 s2, s95, 0x18000
	s_add_i32 s93, 0, 0x20180
	v_writelane_b32 v255, s1, 6
	s_mul_i32 s0, s3, 0xc0
	s_mul_hi_i32 s3, s14, 0xc00
	v_writelane_b32 v255, s2, 7
	s_lshl_b32 s1, s97, 9
	s_lshl_b32 s0, s0, 1
	v_writelane_b32 v255, s3, 8
	s_mul_i32 s2, s95, 0xa8000
	v_writelane_b32 v255, s14, 9
	s_mul_hi_i32 s3, s14, 0x5400
	v_writelane_b32 v255, s2, 10
	s_add_i32 s60, 0, 0x20184
	v_mov_b32_e32 v1, 0x358637bd
	v_writelane_b32 v255, s3, 11
	v_writelane_b32 v255, s1, 12
	s_lshl_b32 s1, s95, 11
	v_writelane_b32 v255, s1, 13
	s_lshl_b32 s1, s95, 4
	v_writelane_b32 v255, s1, 14
	s_lshl_b32 s1, s95, 10
	v_writelane_b32 v255, s1, 15
	s_lshl_b32 s1, s95, 9
	v_writelane_b32 v255, s1, 16
	s_add_i32 s1, 0, 0x20160
	v_writelane_b32 v255, s1, 17
	s_add_i32 s1, 0, 0x20164
	v_writelane_b32 v255, s1, 18
	s_add_i32 s1, 0, 0x2d00
	v_writelane_b32 v255, s1, 19
	v_writelane_b32 v255, s0, 20
	s_add_i32 s64, 0, 0x12600
	s_nop 0
	v_writelane_b32 v255, s1, 21
	s_add_i32 s0, 0, 0xf000
	v_writelane_b32 v255, s0, 22
	s_add_i32 s0, 0, 0x8800
	v_writelane_b32 v255, s0, 23
	v_writelane_b32 v255, s90, 24
	s_nop 1
	v_writelane_b32 v255, s91, 25
	v_writelane_b32 v255, s69, 26
	v_writelane_b32 v255, s88, 27
	s_nop 1
	v_writelane_b32 v255, s89, 28
	v_writelane_b32 v255, s21, 29
	v_writelane_b32 v255, s22, 30
	v_writelane_b32 v255, s23, 31
	v_writelane_b32 v255, s93, 32
	v_writelane_b32 v255, s60, 33
	v_writelane_b32 v255, s92, 34
	s_nop 1
	v_writelane_b32 v255, s93, 35
	s_branch .LBB0_287
